# v17 + hazard fix: one more wait state between v_cmp and the v_cndmask using its mask in the conv block
# baseline (speedup 1.0000x reference)
.Lev_skip_a:
	s_add_i32 s34, s49, 3
	v_sub_u32_e64 v32, 60, s44 clamp
	s_and_b64 s[20:21], exec, s[38:39]
	v_readfirstlane_b32 s20, v32
	s_cselect_b32 s66, s34, s20
	s_lshl_b32 s34, s66, 13
	s_lshl_b32 s67, s66, 14
	s_add_u32 s20, s43, s67
	s_addc_u32 s21, s63, 0
	v_lshl_add_u64 v[36:37], s[20:21], 0, v[120:121]
	global_load_dwordx4 v[32:35], v120, s[20:21]
	v_add_co_u32_e64 v36, s[20:21], s60, v36
	v_lshl_add_u64 v[48:49], v[146:147], 0, s[34:35]
	s_nop 0
	v_addc_co_u32_e64 v37, s[20:21], 0, v37, s[20:21]
	s_add_u32 s20, s64, s67
	s_addc_u32 s21, s65, 0
	v_lshl_add_u64 v[44:45], s[20:21], 0, v[120:121]
	global_load_dwordx4 v[36:39], v[36:37], off
	s_lshl_b32 s34, s66, 10
	global_load_dwordx4 v[40:43], v120, s[20:21]
	v_add_co_u32_e64 v44, s[20:21], s60, v44
	v_lshl_add_u64 v[52:53], v[148:149], 0, s[34:35]
	s_nop 0
	v_addc_co_u32_e64 v45, s[20:21], 0, v45, s[20:21]
	s_lshl_b32 s20, s49, 1
	s_add_i32 s34, s20, 4
	s_waitcnt vmcnt(15)
	v_mov_b32_e32 v214, v64
	v_mov_b32_e32 v215, v65
	v_mov_b32_e32 v216, v66
	v_mov_b32_e32 v217, v67
	v_lshl_add_u64 v[64:65], v[144:145], 0, s[34:35]
	s_add_i32 s34, 0, 0x1e400
	v_mov_b32_e32 v198, v56
	v_mov_b32_e32 v199, v57
	v_mov_b32_e32 v200, v58
	v_mov_b32_e32 v201, v59
	v_mov_b32_e32 v202, v60
	v_mov_b32_e32 v203, v61
	v_mov_b32_e32 v204, v62
	v_mov_b32_e32 v205, v63
	s_waitcnt vmcnt(14)
	v_mov_b32_e32 v242, v68
	v_mov_b32_e32 v243, v69
	v_mov_b32_e32 v244, v70
	v_mov_b32_e32 v245, v71
	v_add_u32_e32 v116, s34, v143
	ds_read_b128 v[190:193], v116
	v_and_b32_e32 v66, 0xfff, v64
	v_cmp_ne_u32_e64 s[20:21], 0, v66
	v_add_u32_e32 v185, 0, v143
	v_add_u32_e32 v116, 0x1e600, v185
	s_waitcnt lgkmcnt(0)
	v_pk_mul_f32 v[192:193], v[98:99], v[192:193]
	v_pk_mul_f32 v[190:191], v[96:97], v[190:191]
	v_pk_mul_f32 v[98:99], v[102:103], v[192:193]
	v_pk_mul_f32 v[96:97], v[100:101], v[190:191]
	v_cndmask_b32_e64 v56, 0, 1, s[20:21]
	v_cvt_pk_bf16_f32 v100, v96, v97
	v_cvt_pk_bf16_f32 v101, v98, v99
	v_sub_co_u32_e64 v56, s[20:21], v64, v56
	ds_read_b128 v[116:119], v116
	ds_write_b64 v182, v[100:101]
	v_pk_mul_f32 v[100:101], v[104:105], v[190:191]
	v_pk_mul_f32 v[102:103], v[106:107], v[192:193]
	v_subbrev_co_u32_e64 v57, s[20:21], 0, v65, s[20:21]
	v_cvt_pk_bf16_f32 v104, v100, v101
	v_cvt_pk_bf16_f32 v105, v102, v103
	v_cmp_ne_u32_e64 s[20:21], s62, v66
	ds_write_b64 v182, v[104:105] offset:4352
	v_pk_mul_f32 v[104:105], v[108:109], v[190:191]
	v_pk_mul_f32 v[106:107], v[110:111], v[192:193]
	v_cndmask_b32_e64 v66, 0, 1, s[20:21]
	v_mov_b32_e32 v67, s35
	v_cvt_pk_bf16_f32 v108, v104, v105
	v_cvt_pk_bf16_f32 v109, v106, v107
	v_lshlrev_b64 v[68:69], 11, v[64:65]
	v_lshl_add_u64 v[64:65], v[64:65], 0, v[66:67]
	ds_write_b64 v182, v[108:109] offset:8704
	v_pk_mul_f32 v[108:109], v[112:113], v[190:191]
	v_pk_mul_f32 v[110:111], v[114:115], v[192:193]
	v_lshlrev_b64 v[56:57], 11, v[56:57]
	v_lshlrev_b64 v[64:65], 11, v[64:65]
	v_cvt_pk_bf16_f32 v112, v108, v109
	v_cvt_pk_bf16_f32 v113, v110, v111
	v_lshl_add_u64 v[56:57], v[134:135], 0, v[56:57]
	v_lshl_add_u64 v[60:61], v[134:135], 0, v[68:69]
	v_lshl_add_u64 v[64:65], v[134:135], 0, v[64:65]
	v_lshl_add_u64 v[68:69], v[136:137], 0, v[68:69]
	ds_write_b64 v182, v[112:113] offset:13056
	global_load_dwordx4 v[44:47], v[44:45], off
	global_load_dwordx4 v[48:51], v[48:49], off
	global_load_dwordx4 v[52:55], v[52:53], off
	global_load_dwordx4 v[56:59], v[56:57], off
	s_lshl_b32 s48, s48, 6
	global_load_dwordx4 v[60:63], v[60:61], off
	s_nop 0
	global_load_dwordx4 v[64:67], v[64:65], off
	s_nop 0
	global_load_dwordx4 v[68:71], v[68:69], off
	s_waitcnt lgkmcnt(0)
	s_barrier
	ds_read_b128 v[218:221], v170 offset:61440
	ds_read_b128 v[222:225], v171 offset:44032
	ds_read_b128 v[226:229], v172 offset:44032
	ds_read_b128 v[230:233], v170 offset:61504
	ds_read_b128 v[234:237], v171 offset:44096
	ds_read_b128 v[238:241], v172 offset:44096
	v_and_b32_e32 v250, 0xfff, v184
	v_cmp_ne_u32_e64 s[20:21], 0, v250
	v_add_u32_e32 v184, 4, v184
	s_nop 0
	v_cndmask_b32_e64 v198, 0, v198, s[20:21]
	v_cndmask_b32_e64 v199, 0, v199, s[20:21]
	v_cndmask_b32_e64 v200, 0, v200, s[20:21]
	v_cndmask_b32_e64 v201, 0, v201, s[20:21]
	v_cmp_ne_u32_e64 s[20:21], s62, v250
	v_lshlrev_b32_e32 v246, 16, v202
	v_and_b32_e32 v247, 0xffff0000, v202
	v_cndmask_b32_e64 v214, 0, v214, s[20:21]
	v_cndmask_b32_e64 v215, 0, v215, s[20:21]
	v_cndmask_b32_e64 v216, 0, v216, s[20:21]
	v_cndmask_b32_e64 v217, 0, v217, s[20:21]
	v_pk_mul_f32 v[246:247], v[8:9], v[246:247]
	v_lshlrev_b32_e32 v248, 16, v198
	v_and_b32_e32 v249, 0xffff0000, v198
	v_pk_fma_f32 v[246:247], v[0:1], v[248:249], v[246:247]
	v_lshlrev_b32_e32 v248, 16, v214
	v_and_b32_e32 v249, 0xffff0000, v214
	v_pk_fma_f32 v[246:247], v[16:17], v[248:249], v[246:247]
	v_pk_add_f32 v[246:247], v[24:25], v[246:247]
	v_lshlrev_b32_e32 v248, 16, v242
	v_and_b32_e32 v249, 0xffff0000, v242
	v_pk_mul_f32 v[246:247], v[246:247], v[248:249]
	v_cvt_pk_bf16_f32 v198, v246, v247
	v_lshlrev_b32_e32 v246, 16, v203
	v_and_b32_e32 v247, 0xffff0000, v203
	v_pk_mul_f32 v[246:247], v[10:11], v[246:247]
	v_lshlrev_b32_e32 v248, 16, v199
	v_and_b32_e32 v249, 0xffff0000, v199
	v_pk_fma_f32 v[246:247], v[2:3], v[248:249], v[246:247]
	v_lshlrev_b32_e32 v248, 16, v215
	v_and_b32_e32 v249, 0xffff0000, v215
	v_pk_fma_f32 v[246:247], v[18:19], v[248:249], v[246:247]
	v_pk_add_f32 v[246:247], v[26:27], v[246:247]
	v_lshlrev_b32_e32 v248, 16, v243
	v_and_b32_e32 v249, 0xffff0000, v243
	v_pk_mul_f32 v[246:247], v[246:247], v[248:249]
	v_cvt_pk_bf16_f32 v199, v246, v247
	v_lshlrev_b32_e32 v246, 16, v204
	v_and_b32_e32 v247, 0xffff0000, v204
	v_pk_mul_f32 v[246:247], v[12:13], v[246:247]
	v_lshlrev_b32_e32 v248, 16, v200
	v_and_b32_e32 v249, 0xffff0000, v200
	v_pk_fma_f32 v[246:247], v[4:5], v[248:249], v[246:247]
	v_lshlrev_b32_e32 v248, 16, v216
	v_and_b32_e32 v249, 0xffff0000, v216
	v_pk_fma_f32 v[246:247], v[20:21], v[248:249], v[246:247]
	v_pk_add_f32 v[246:247], v[28:29], v[246:247]
	v_lshlrev_b32_e32 v248, 16, v244
	v_and_b32_e32 v249, 0xffff0000, v244
	v_pk_mul_f32 v[246:247], v[246:247], v[248:249]
	v_cvt_pk_bf16_f32 v200, v246, v247
	v_lshlrev_b32_e32 v246, 16, v205
	v_and_b32_e32 v247, 0xffff0000, v205
	v_pk_mul_f32 v[246:247], v[14:15], v[246:247]
	v_lshlrev_b32_e32 v248, 16, v201
	v_and_b32_e32 v249, 0xffff0000, v201
	v_pk_fma_f32 v[246:247], v[6:7], v[248:249], v[246:247]
	v_lshlrev_b32_e32 v248, 16, v217
	v_and_b32_e32 v249, 0xffff0000, v217
	v_pk_fma_f32 v[246:247], v[22:23], v[248:249], v[246:247]
	v_pk_add_f32 v[246:247], v[30:31], v[246:247]
	v_lshlrev_b32_e32 v248, 16, v245
	v_and_b32_e32 v249, 0xffff0000, v245
	v_pk_mul_f32 v[246:247], v[246:247], v[248:249]
	v_cvt_pk_bf16_f32 v201, v246, v247
	global_store_dwordx4 v[152:153], v[198:201], off
	ds_read_b128 v[242:245], v170 offset:61568
	ds_read_b128 v[246:249], v171 offset:44160
	ds_read_b128 v[250:253], v172 offset:44160
	s_waitcnt lgkmcnt(6)
	v_mfma_f32_16x16x32_bf16 v[190:193], v[218:221], v[222:225], 0
	v_mfma_f32_16x16x32_bf16 v[194:197], v[218:221], v[226:229], 0
	ds_read_b128 v[218:221], v170 offset:61632
	ds_read_b128 v[222:225], v171 offset:44224
	ds_read_b128 v[226:229], v172 offset:44224
	s_waitcnt lgkmcnt(6)
	v_mfma_f32_16x16x32_bf16 v[190:193], v[230:233], v[234:237], v[190:193]
	v_mfma_f32_16x16x32_bf16 v[194:197], v[230:233], v[238:241], v[194:197]
	ds_read_b64_tr_b16 v[230:231], v206 offset:34816
	ds_read_b64_tr_b16 v[232:233], v206 offset:35392
	ds_read_b128 v[234:237], v208
	ds_read_b128 v[238:241], v209
	s_waitcnt lgkmcnt(7)
	v_mfma_f32_16x16x32_bf16 v[190:193], v[242:245], v[246:249], v[190:193]
	v_mfma_f32_16x16x32_bf16 v[194:197], v[242:245], v[250:253], v[194:197]
	ds_read_b64_tr_b16 v[242:243], v206 offset:39424
	ds_read_b64_tr_b16 v[244:245], v206 offset:40000
	ds_read_b128 v[246:249], v208 offset:64
	ds_read_b128 v[250:253], v209 offset:64
	s_waitcnt lgkmcnt(8)
	v_mfma_f32_16x16x32_bf16 v[190:193], v[218:221], v[222:225], v[190:193]
	v_mfma_f32_16x16x32_bf16 v[194:197], v[218:221], v[226:229], v[194:197]
	ds_read_b128 v[218:221], v183
	ds_read_b128 v[222:225], v171
	ds_read_b128 v[226:229], v172
	s_waitcnt lgkmcnt(7)
	v_mfma_f32_16x16x32_bf16 v[198:201], v[230:233], v[234:237], 0
	v_mfma_f32_16x16x32_bf16 v[202:205], v[230:233], v[238:241], 0
	ds_read_b128 v[230:233], v183 offset:64
	ds_read_b128 v[234:237], v171 offset:64
	ds_read_b128 v[238:241], v172 offset:64
	s_waitcnt lgkmcnt(6)
	v_mfma_f32_16x16x32_bf16 v[198:201], v[242:245], v[246:249], v[198:201]
	v_mfma_f32_16x16x32_bf16 v[202:205], v[242:245], v[250:253], v[202:205]
	ds_read_b128 v[242:245], v183 offset:128
	ds_read_b128 v[246:249], v171 offset:128
	ds_read_b128 v[250:253], v172 offset:128
	v_cndmask_b32_e32 v190, 0, v190, vcc
	v_cndmask_b32_e64 v191, 0, v191, s[6:7]
	v_cndmask_b32_e64 v192, 0, v192, s[8:9]
	v_cndmask_b32_e64 v193, 0, v193, s[10:11]
	v_cvt_pk_bf16_f32 v190, v190, v191
	v_cvt_pk_bf16_f32 v191, v192, v193
	v_cndmask_b32_e64 v194, 0, v194, s[12:13]
	v_cndmask_b32_e64 v195, 0, v195, s[14:15]
	v_cndmask_b32_e64 v196, 0, v196, s[16:17]
	v_cndmask_b32_e64 v197, 0, v197, s[18:19]
	v_cvt_pk_bf16_f32 v194, v194, v195
	v_cvt_pk_bf16_f32 v195, v196, v197
	ds_write_b64 v212, v[190:191]
	ds_write_b64 v213, v[194:195]
	s_waitcnt lgkmcnt(8)
	v_mfma_f32_16x16x32_bf16 v[198:201], v[218:221], v[222:225], v[198:201]
	v_mfma_f32_16x16x32_bf16 v[202:205], v[218:221], v[226:229], v[202:205]
	ds_read_b64_tr_b16 v[190:191], v178 offset:17408
	ds_read_b64_tr_b16 v[192:193], v178 offset:18496
	ds_read_b64_tr_b16 v[194:195], v178 offset:26112
	ds_read_b64_tr_b16 v[196:197], v178 offset:27200
	s_waitcnt lgkmcnt(9)
	v_mfma_f32_16x16x32_bf16 v[198:201], v[230:233], v[234:237], v[198:201]
	v_mfma_f32_16x16x32_bf16 v[202:205], v[230:233], v[238:241], v[202:205]
	ds_read_b128 v[230:233], v183 offset:192
	ds_read_b128 v[234:237], v171 offset:192
	ds_read_b128 v[238:241], v172 offset:192
	s_waitcnt lgkmcnt(9)
	v_mfma_f32_16x16x32_bf16 v[198:201], v[242:245], v[246:249], v[198:201]
	v_mfma_f32_16x16x32_bf16 v[202:205], v[242:245], v[250:253], v[202:205]
	ds_read_b64_tr_b16 v[242:243], v161 offset:34816
	ds_read_b64_tr_b16 v[244:245], v161 offset:35392
	ds_read_b64_tr_b16 v[246:247], v161 offset:34848
	ds_read_b64_tr_b16 v[248:249], v161 offset:35424
	s_waitcnt lgkmcnt(7)
	ds_read_b64_tr_b16 v[218:219], v161 offset:34880
	ds_read_b64_tr_b16 v[220:221], v161 offset:35456
	ds_read_b64_tr_b16 v[222:223], v161 offset:34912
	ds_read_b64_tr_b16 v[224:225], v161 offset:35488
	s_waitcnt lgkmcnt(8)
	v_mfma_f32_16x16x32_bf16 v[198:201], v[230:233], v[234:237], v[198:201]
	v_mfma_f32_16x16x32_bf16 v[202:205], v[230:233], v[238:241], v[202:205]
	ds_read_b64_tr_b16 v[230:231], v161 offset:39424
	ds_read_b64_tr_b16 v[232:233], v161 offset:40000
	ds_read_b64_tr_b16 v[234:235], v161 offset:39456
	ds_read_b64_tr_b16 v[236:237], v161 offset:40032
	s_waitcnt lgkmcnt(8)
	v_mfma_f32_16x16x32_bf16 v[96:99], v[190:193], v[242:245], v[96:99]
	v_mfma_f32_16x16x32_bf16 v[100:103], v[190:193], v[246:249], v[100:103]
	ds_read_b64_tr_b16 v[242:243], v161 offset:39488
	ds_read_b64_tr_b16 v[244:245], v161 offset:40064
	ds_read_b64_tr_b16 v[246:247], v161 offset:39520
	ds_read_b64_tr_b16 v[248:249], v161 offset:40096
	v_cvt_pk_bf16_f32 v198, v198, v199
	v_cvt_pk_bf16_f32 v199, v200, v201
	v_add_u32_e32 v254, s48, v173
	v_mad_u64_u32 v[254:255], s[20:21], v254, s42, 0
	v_lshl_add_u64 v[254:255], v[254:255], 1, v[150:151]
	v_cvt_pk_bf16_f32 v202, v202, v203
	v_cvt_pk_bf16_f32 v203, v204, v205
	global_store_dwordx2 v[254:255], v[198:199], off
	v_add_u32_e32 v254, s48, v179
	v_mad_u64_u32 v[254:255], s[20:21], v254, s42, 0
	v_lshl_add_u64 v[254:255], v[254:255], 1, v[150:151]
	global_store_dwordx2 v[254:255], v[202:203], off
	s_waitcnt lgkmcnt(8)
	v_mfma_f32_16x16x32_bf16 v[104:107], v[190:193], v[218:221], v[104:107]
	v_mfma_f32_16x16x32_bf16 v[214:217], v[190:193], v[222:225], v[108:111]
	s_waitcnt lgkmcnt(4)
	v_mfma_f32_16x16x32_bf16 v[112:115], v[194:197], v[230:233], v[96:99]
	v_mfma_f32_16x16x32_bf16 v[108:111], v[194:197], v[234:237], v[100:103]
	s_waitcnt lgkmcnt(0)
	v_mfma_f32_16x16x32_bf16 v[104:107], v[194:197], v[242:245], v[104:107]
	v_mfma_f32_16x16x32_bf16 v[100:103], v[194:197], v[246:249], v[214:217]
	s_min_u32 s20, s44, 59
	s_waitcnt lgkmcnt(0)
	s_barrier
	s_waitcnt vmcnt(20)
	ds_write_b128 v168, v[72:75]
	s_waitcnt vmcnt(19)
	ds_write_b128 v168, v[80:83] offset:8704
	s_waitcnt vmcnt(18)
	ds_write_b128 v168, v[76:79] offset:17408
	s_waitcnt vmcnt(17)
	ds_write_b128 v168, v[84:87] offset:26112
	s_waitcnt vmcnt(16)
	ds_write_b128 v169, v[88:91] offset:34816
	v_add_u32_e32 v72, s34, v154
	s_add_i32 s34, s20, 4
	s_waitcnt vmcnt(15)
	s_cmp_lg_u32 s69, 0
	s_cbranch_scc1 .Lev_skip_b
	ds_write_b128 v72, v[92:95]
